# speedup vs baseline: 1.0752x; 1.0512x over previous
.LBB0_68:
	s_ashr_i32 s11, s10, 31
	s_lshl_b64 s[10:11], s[10:11], 3
	s_add_u32 s10, s64, s10
	s_addc_u32 s11, s65, s11
	s_waitcnt lgkmcnt(0)
	s_load_dwordx2 s[22:23], s[10:11], 0x0
	s_movk_i32 s2, 0x2000
	v_cmp_gt_i32_e32 vcc, s2, v4
	s_waitcnt lgkmcnt(0)
	s_barrier
	s_and_saveexec_b64 s[10:11], vcc
	s_cbranch_execz .LBB0_71
	v_and_b32_e32 v5, 31, v4
	v_lshlrev_b32_e32 v0, 3, v5
	v_lshl_add_u64 v[2:3], s[8:9], 0, v[0:1]
	v_and_b32_e32 v0, 3, v5
	v_lshlrev_b32_e32 v0, 2, v0
	v_lshrrev_b32_e32 v11, 2, v5
	s_mov_b64 s[8:9], 0
	v_mov_b32_e32 v5, v4
.LBB0_70:
	v_ashrrev_i32_e32 v6, 5, v5
	v_ashrrev_i32_e32 v7, 31, v6
	v_lshlrev_b64 v[8:9], 8, v[6:7]
	v_lshl_add_u64 v[8:9], v[2:3], 0, v[8:9]
	global_load_dwordx2 v[8:9], v[8:9], off
	v_and_b32_e32 v7, 0x3ffff000, v5
	s_movk_i32 s2, 0x1eff
	v_and_b32_e32 v12, 0x7f, v6
	v_add_u32_e32 v10, 0x100, v5
	v_cmp_lt_i32_e32 vcc, s2, v5
	v_lshlrev_b32_e32 v12, 7, v12
	v_and_b32_e32 v6, 7, v6
	v_lshl_add_u32 v7, v7, 2, v12
	v_xor_b32_e32 v6, v6, v11
	s_or_b64 s[8:9], vcc, s[8:9]
	v_mov_b32_e32 v5, v10
	v_lshl_add_u32 v6, v6, 4, v7
	v_add_u32_e32 v6, v6, v0
	s_waitcnt vmcnt(0)
	v_cvt_pk_bf16_f32 v7, v8, v9
	ds_write_b32 v6, v7
	s_andn2_b64 exec, exec, s[8:9]
	s_cbranch_execnz .LBB0_70

.LBB0_135:
	s_or_b64 exec, exec, s[18:19]
	s_and_saveexec_b64 s[10:11], s[8:9]
	v_lshlrev_b32_e32 v0, 4, v8
	s_movk_i32 s2, 0x100
	v_or3_b32 v6, v0, v7, s2
	s_or_b64 exec, exec, s[10:11]
	v_ashrrev_i32_e32 v0, 6, v4
	v_add_u32_e32 v226, s35, v0
	s_movk_i32 s2, 0x4000
	v_cmp_gt_i32_e32 vcc, s2, v226
	s_and_saveexec_b64 s[8:9], vcc
	s_cbranch_execz .LBB0_213
	v_readlane_b32 s12, v254, 29
	s_movk_i32 s2, 0xe00
	v_readlane_b32 s14, v254, 31
	s_waitcnt vmcnt(1)
	v_mul_lo_u32 v12, v0, s2
	v_readlane_b32 s15, v254, 32
	s_add_u32 s2, s14, s6
	s_addc_u32 s10, s15, s7
	s_add_u32 s6, s2, 0x187c0000
	s_addc_u32 s7, s10, 0
	v_readlane_b32 s13, v254, 30
	s_add_u32 s12, s2, 0x1c7c0000
	s_addc_u32 s13, s10, 0
	s_add_u32 s14, s2, 0x1e7c0000
	s_addc_u32 s15, s10, 0
	s_add_u32 s16, s2, 0x27c0000
	s_addc_u32 s17, s10, 0
	s_add_u32 s18, s2, 0x147c0000
	s_addc_u32 s19, s10, 0
	s_add_u32 s20, s2, 0x107c0000
	s_addc_u32 s21, s10, 0
	s_mov_b32 s10, 0
	v_cvt_f64_u32_e32 v[8:9], v226
	s_mov_b32 s11, 0x40cfff80
	v_min_f64 v[8:9], v[8:9], s[10:11]
	v_cvt_i32_f64_e32 v8, v[8:9]
	v_ashrrev_i32_e32 v9, 31, v8
	v_and_b32_e32 v7, 63, v4
	v_lshlrev_b64 v[8:9], 12, v[8:9]
	v_lshl_add_u64 v[8:9], s[6:7], 0, v[8:9]
	v_lshlrev_b32_e32 v10, 3, v7
	v_mov_b32_e32 v11, v1
	v_lshl_add_u64 v[8:9], v[8:9], 0, v[10:11]
	global_load_dwordx2 v[96:97], v[8:9], off offset:3584
	global_load_dwordx2 v[98:99], v[8:9], off offset:3072
	global_load_dwordx2 v[100:101], v[8:9], off offset:2560
	global_load_dwordx2 v[102:103], v[8:9], off offset:2048
	global_load_dwordx2 v[104:105], v[8:9], off offset:1536
	global_load_dwordx2 v[106:107], v[8:9], off offset:1024
	global_load_dwordx2 v[108:109], v[8:9], off offset:512
	global_load_dwordx2 v[110:111], v[8:9], off
	v_and_b32_e32 v0, 64, v180
	v_lshlrev_b32_e32 v8, 7, v83
	v_mov_b32_e32 v9, v1
	v_lshlrev_b32_e32 v14, 3, v83
	v_and_or_b32 v156, v4, 48, v0
	v_lshl_add_u64 v[88:89], s[22:23], 0, v[8:9]
	v_and_b32_e32 v8, 15, v2
	v_xor_b32_e32 v155, 0x7f, v83
	v_xor_b32_e32 v159, 0x6f, v83
	v_xor_b32_e32 v160, 0x5f, v83
	v_xor_b32_e32 v161, 0x4f, v83
	v_xor_b32_e32 v162, 0x3f, v83
	v_xor_b32_e32 v163, 0x2f, v83
	v_xor_b32_e32 v164, 0x1f, v83
	v_xor_b32_e32 v165, 0xf, v83
	v_bfe_u32 v9, v2, 4, 4
	v_or_b32_e32 v14, v156, v8
	v_lshlrev_b32_e32 v166, 2, v14
	v_or_b32_e32 v14, v156, v9
	v_lshlrev_b32_e32 v167, 2, v14
	v_and_b32_e32 v2, 0x100, v2
	v_and_b32_e32 v14, 15, v3
	v_cmp_ne_u32_e64 s[46:47], 0, v2
	v_bfe_u32 v15, v3, 4, 4
	v_or_b32_e32 v2, v156, v14
	v_lshlrev_b32_e32 v168, 2, v2
	v_or_b32_e32 v2, v156, v15
	v_lshlrev_b32_e32 v169, 2, v2
	v_and_b32_e32 v2, 0x100, v3
	s_waitcnt vmcnt(8)
	v_and_b32_e32 v16, 15, v5
	v_cmp_ne_u32_e64 s[48:49], 0, v2
	v_bfe_u32 v17, v5, 4, 4
	v_or_b32_e32 v2, v156, v16
	v_lshlrev_b32_e32 v203, 2, v2
	v_or_b32_e32 v2, v156, v17
	v_lshlrev_b32_e32 v204, 2, v2
	v_and_b32_e32 v2, 0x100, v5
	v_and_b32_e32 v5, 15, v6
	v_cmp_ne_u32_e64 s[50:51], 0, v2
	v_bfe_u32 v18, v6, 4, 4
	v_or_b32_e32 v2, v156, v5
	v_lshlrev_b32_e32 v205, 2, v2
	v_or_b32_e32 v2, v156, v18
	v_lshlrev_b32_e32 v206, 2, v2
	v_and_b32_e32 v2, 0x100, v6
	v_cmp_lt_i32_e32 vcc, v183, v182
	v_cmp_ne_u32_e64 s[52:53], 0, v2
	v_bfe_u32 v125, v4, 4, 2
	v_cndmask_b32_e32 v2, v180, v183, vcc
	v_cmp_lt_i32_e32 vcc, v184, v182
	v_lshlrev_b32_e32 v207, 2, v2
	v_lshl_add_u32 v13, v125, 8, v12
	v_cndmask_b32_e32 v2, v180, v184, vcc
	v_cmp_lt_i32_e32 vcc, v185, v182
	v_lshlrev_b32_e32 v208, 2, v2
	s_cmp_gt_i32 s0, 2
	v_cndmask_b32_e32 v2, v180, v185, vcc
	v_cmp_lt_i32_e32 vcc, v186, v182
	v_lshlrev_b32_e32 v209, 2, v2
	v_mov_b32_e32 v3, v1
	v_cndmask_b32_e32 v2, v180, v186, vcc
	v_cmp_lt_i32_e32 vcc, v187, v182
	v_lshlrev_b32_e32 v210, 2, v2
	s_movk_i32 s0, 0xff04
	v_cndmask_b32_e32 v2, v180, v187, vcc
	v_cmp_lt_i32_e32 vcc, v188, v182
	v_lshlrev_b32_e32 v211, 2, v2
	v_lshlrev_b32_e32 v82, 5, v83
	v_cndmask_b32_e32 v2, v180, v188, vcc
	v_lshlrev_b32_e32 v212, 2, v2
	v_lshlrev_b32_e32 v2, 6, v83
	v_mul_i32_i24_e32 v4, 0xffffff04, v125
	v_lshlrev_b32_e32 v0, 4, v83
	v_lshl_add_u64 v[90:91], s[16:17], 0, v[2:3]
	v_lshl_or_b32 v217, v125, 2, v12
	v_mad_i32_i24 v2, v125, s0, v13
	v_lshl_or_b32 v154, v7, 2, v12
	v_mov_b32_e32 v158, 0
	v_lshlrev_b32_e32 v157, 2, v156
	v_lshl_add_u64 v[84:85], s[12:13], 0, v[0:1]
	v_cmp_eq_u32_e64 s[44:45], 0, v83
	v_lshl_add_u64 v[86:87], s[14:15], 0, v[0:1]
	s_cselect_b64 s[22:23], -1, 0
	v_cmp_gt_u32_e64 s[54:55], 16, v7
	v_lshl_or_b32 v213, v8, 4, v9
	v_lshl_or_b32 v214, v14, 4, v15
	v_lshl_or_b32 v215, v16, 4, v17
	v_lshl_or_b32 v216, v5, 4, v18
	v_lshl_add_u64 v[92:93], s[6:7], 0, v[10:11]
	v_add_u32_e32 v218, 0x8000, v13
	v_add_u32_e32 v219, 0x8080, v13
	v_or_b32_e32 v220, 0x4000, v82
	v_add_u32_e32 v221, 0x8c00, v2
	v_add_u32_e32 v222, 0x8a30, v217
	v_add_u32_e32 v223, 0x8800, v2
	s_mov_b64 s[58:59], 0
	v_add_u32_e32 v224, v13, v4
	v_mov_b32_e32 v225, 0
	s_branch .LBB0_141

.LBB0_141:
	s_waitcnt vmcnt(0)
	v_cvt_pk_bf16_f32 v2, v110, v111
	v_cvt_pk_bf16_f32 v3, v108, v109
	ds_write2st64_b32 v154, v2, v3 offset0:128 offset1:129
	v_cvt_pk_bf16_f32 v2, v106, v107
	v_cvt_pk_bf16_f32 v3, v104, v105
	ds_write2st64_b32 v154, v2, v3 offset0:130 offset1:131
	v_cvt_pk_bf16_f32 v2, v102, v103
	v_cvt_pk_bf16_f32 v3, v100, v101
	ds_write2st64_b32 v154, v2, v3 offset0:132 offset1:133
	v_cvt_pk_bf16_f32 v2, v98, v99
	v_cvt_pk_bf16_f32 v3, v96, v97
	v_ashrrev_i32_e32 v95, 31, v226
	v_mov_b32_e32 v94, v226
	ds_write2st64_b32 v154, v2, v3 offset0:134 offset1:135
	v_lshlrev_b64 v[2:3], 11, v[94:95]
	v_lshl_add_u64 v[2:3], v[90:91], 0, v[2:3]
	global_load_dwordx4 v[38:41], v[2:3], off offset:48
	global_load_dwordx4 v[46:49], v[2:3], off offset:32
	global_load_dwordx4 v[50:53], v[2:3], off offset:16
	global_load_dwordx4 v[54:57], v[2:3], off
	global_load_dwordx4 v[26:29], v[2:3], off offset:1072
	global_load_dwordx4 v[30:33], v[2:3], off offset:1056
	global_load_dwordx4 v[34:37], v[2:3], off offset:1040
	global_load_dwordx4 v[42:45], v[2:3], off offset:1024
	v_lshlrev_b32_e32 v61, 2, v180
	v_sub_u32_e32 v58, v154, v61
	v_and_b32_e32 v61, 1, v83
	v_lshl_add_u32 v58, v61, 10, v58
	v_lshrrev_b32_e32 v61, 2, v83
	v_lshl_add_u32 v58, v61, 8, v58
	v_lshrrev_b32_e32 v61, 4, v180
	v_lshl_add_u32 v58, v61, 4, v58
	v_and_b32_e32 v59, 7, v83
	v_xor_b32_e32 v59, v59, v61
	v_lshlrev_b32_e32 v59, 4, v59
	v_lshl_add_u32 v59, v83, 7, v59
	v_xor_b32_e32 v60, 64, v59
	ds_read_b128 v[62:65], v58 offset:32768
	ds_read_b128 v[66:69], v58 offset:32832
	ds_read_b128 v[70:73], v58 offset:32896
	ds_read_b128 v[74:77], v58 offset:32960
	ds_read_b128 v[78:81], v59 offset:0
	ds_read_b128 v[196:199], v60 offset:0
	ds_read_b128 v[230:233], v59 offset:2048
	ds_read_b128 v[234:237], v60 offset:2048
	s_waitcnt lgkmcnt(2)
	v_mfma_f32_16x16x32_bf16 v[112:115], v[62:65], v[78:81], 0
	v_mfma_f32_16x16x32_bf16 v[112:115], v[66:69], v[196:199], v[112:115]
	ds_read_b128 v[78:81], v59 offset:4096
	ds_read_b128 v[196:199], v60 offset:4096
	s_waitcnt lgkmcnt(2)
	v_mfma_f32_16x16x32_bf16 v[116:119], v[62:65], v[230:233], 0
	v_mfma_f32_16x16x32_bf16 v[116:119], v[66:69], v[234:237], v[116:119]
	ds_read_b128 v[230:233], v59 offset:6144
	ds_read_b128 v[234:237], v60 offset:6144
	s_waitcnt lgkmcnt(2)
	v_mfma_f32_16x16x32_bf16 v[120:123], v[62:65], v[78:81], 0
	v_mfma_f32_16x16x32_bf16 v[120:123], v[66:69], v[196:199], v[120:123]
	ds_read_b128 v[78:81], v59 offset:8192
	ds_read_b128 v[196:199], v60 offset:8192
	s_waitcnt lgkmcnt(2)
	v_mfma_f32_16x16x32_bf16 v[126:129], v[62:65], v[230:233], 0
	v_mfma_f32_16x16x32_bf16 v[126:129], v[66:69], v[234:237], v[126:129]
	ds_read_b128 v[230:233], v59 offset:10240
	ds_read_b128 v[234:237], v60 offset:10240
	s_waitcnt lgkmcnt(2)
	v_mfma_f32_16x16x32_bf16 v[130:133], v[62:65], v[78:81], 0
	v_mfma_f32_16x16x32_bf16 v[130:133], v[66:69], v[196:199], v[130:133]
	ds_read_b128 v[78:81], v59 offset:12288
	ds_read_b128 v[196:199], v60 offset:12288
	s_waitcnt lgkmcnt(2)
	v_mfma_f32_16x16x32_bf16 v[134:137], v[62:65], v[230:233], 0
	v_mfma_f32_16x16x32_bf16 v[134:137], v[66:69], v[234:237], v[134:137]
	ds_read_b128 v[230:233], v59 offset:14336
	ds_read_b128 v[234:237], v60 offset:14336
	s_waitcnt lgkmcnt(2)
	v_mfma_f32_16x16x32_bf16 v[138:141], v[62:65], v[78:81], 0
	v_mfma_f32_16x16x32_bf16 v[138:141], v[66:69], v[196:199], v[138:141]
	ds_read_b128 v[78:81], v59 offset:16384
	ds_read_b128 v[196:199], v60 offset:16384
	s_waitcnt lgkmcnt(2)
	v_mfma_f32_16x16x32_bf16 v[142:145], v[62:65], v[230:233], 0
	v_mfma_f32_16x16x32_bf16 v[142:145], v[66:69], v[234:237], v[142:145]
	ds_read_b128 v[230:233], v59 offset:18432
	ds_read_b128 v[234:237], v60 offset:18432
	s_waitcnt lgkmcnt(2)
	v_mfma_f32_16x16x32_bf16 v[146:149], v[70:73], v[78:81], 0
	v_mfma_f32_16x16x32_bf16 v[146:149], v[74:77], v[196:199], v[146:149]
	ds_read_b128 v[78:81], v59 offset:20480
	ds_read_b128 v[196:199], v60 offset:20480
	s_waitcnt lgkmcnt(2)
	v_mfma_f32_16x16x32_bf16 v[150:153], v[70:73], v[230:233], 0
	v_mfma_f32_16x16x32_bf16 v[150:153], v[74:77], v[234:237], v[150:153]
	ds_read_b128 v[230:233], v59 offset:22528
	ds_read_b128 v[234:237], v60 offset:22528
	s_waitcnt lgkmcnt(2)
	v_mfma_f32_16x16x32_bf16 v[98:101], v[70:73], v[78:81], 0
	v_mfma_f32_16x16x32_bf16 v[98:101], v[74:77], v[196:199], v[98:101]
	ds_read_b128 v[78:81], v59 offset:24576
	ds_read_b128 v[196:199], v60 offset:24576
	s_waitcnt lgkmcnt(2)
	v_mfma_f32_16x16x32_bf16 v[102:105], v[70:73], v[230:233], 0
	v_mfma_f32_16x16x32_bf16 v[102:105], v[74:77], v[234:237], v[102:105]
	ds_read_b128 v[230:233], v59 offset:26624
	ds_read_b128 v[234:237], v60 offset:26624
	s_waitcnt lgkmcnt(2)
	v_mfma_f32_16x16x32_bf16 v[106:109], v[70:73], v[78:81], 0
	v_mfma_f32_16x16x32_bf16 v[106:109], v[74:77], v[196:199], v[106:109]
	ds_read_b128 v[78:81], v59 offset:28672
	ds_read_b128 v[196:199], v60 offset:28672
	s_waitcnt lgkmcnt(2)
	v_mfma_f32_16x16x32_bf16 v[238:241], v[70:73], v[230:233], 0
	v_mfma_f32_16x16x32_bf16 v[238:241], v[74:77], v[234:237], v[238:241]
	ds_read_b128 v[230:233], v59 offset:30720
	ds_read_b128 v[234:237], v60 offset:30720
	s_waitcnt lgkmcnt(2)
	v_mfma_f32_16x16x32_bf16 v[242:245], v[70:73], v[78:81], 0
	v_mfma_f32_16x16x32_bf16 v[242:245], v[74:77], v[196:199], v[242:245]
	s_waitcnt lgkmcnt(0)
	v_mfma_f32_16x16x32_bf16 v[246:249], v[70:73], v[230:233], 0
	v_mfma_f32_16x16x32_bf16 v[246:249], v[74:77], v[234:237], v[246:249]
	s_mov_b32 s0, 0
	s_mov_b64 s[6:7], -1
.LBB0_142:
	s_xor_b64 s[60:61], s[6:7], -1
	v_cndmask_b32_e64 v12, v112, v113, s[60:61]
	v_cndmask_b32_e64 v13, v116, v117, s[60:61]
	v_cndmask_b32_e64 v11, v120, v121, s[60:61]
	v_cndmask_b32_e64 v10, v126, v127, s[60:61]
	v_cndmask_b32_e64 v9, v130, v131, s[60:61]
	v_cndmask_b32_e64 v8, v134, v135, s[60:61]
	v_cndmask_b32_e64 v7, v138, v139, s[60:61]
	v_cndmask_b32_e64 v6, v142, v143, s[60:61]
	v_cndmask_b32_e64 v19, v146, v147, s[60:61]
	v_cndmask_b32_e64 v21, v150, v151, s[60:61]
	v_cndmask_b32_e64 v20, v98, v99, s[60:61]
	v_cndmask_b32_e64 v18, v102, v103, s[60:61]
	v_cndmask_b32_e64 v17, v106, v107, s[60:61]
	v_cndmask_b32_e64 v16, v238, v239, s[60:61]
	v_cndmask_b32_e64 v15, v242, v243, s[60:61]
	v_cndmask_b32_e64 v14, v246, v247, s[60:61]
	v_ashrrev_i32_e32 v5, 31, v10
	v_bitop3_b32 v5, v5, v10, s27 bitop3:0x36
	v_ashrrev_i32_e32 v10, 31, v9
	v_bitop3_b32 v9, v10, v9, s27 bitop3:0x36
	v_ashrrev_i32_e32 v10, 31, v8
	v_bitop3_b32 v8, v10, v8, s27 bitop3:0x36
	v_ashrrev_i32_e32 v10, 31, v7
	v_ashrrev_i32_e32 v2, 31, v12
	v_ashrrev_i32_e32 v3, 31, v13
	v_ashrrev_i32_e32 v4, 31, v11
	v_bitop3_b32 v7, v10, v7, s27 bitop3:0x36
	v_ashrrev_i32_e32 v10, 31, v6
	v_bitop3_b32 v2, v2, v12, s27 bitop3:0x36
	v_bitop3_b32 v3, v3, v13, s27 bitop3:0x36
	v_bitop3_b32 v4, v4, v11, s27 bitop3:0x36
	v_bitop3_b32 v6, v10, v6, s27 bitop3:0x36
	v_and_or_b32 v2, v2, s40, v155
	v_and_or_b32 v3, v3, s40, v159
	v_and_or_b32 v4, v4, s40, v160
	v_and_or_b32 v5, v5, s40, v161
	v_and_or_b32 v9, v9, s40, v162
	v_and_or_b32 v8, v8, s40, v163
	v_and_or_b32 v7, v7, s40, v164
	v_and_or_b32 v6, v6, s40, v165
	v_max_u32_e32 v10, v2, v3
	v_min_u32_e32 v2, v2, v3
	v_max_u32_e32 v3, v4, v5
	v_min_u32_e32 v4, v4, v5
	v_max_u32_e32 v5, v9, v8
	v_min_u32_e32 v8, v9, v8
	v_max_u32_e32 v9, v7, v6
	v_min_u32_e32 v6, v7, v6
	v_max_u32_e32 v7, v10, v3
	v_min_u32_e32 v3, v10, v3
	v_max_u32_e32 v10, v2, v4
	v_min_u32_e32 v11, v2, v4
	v_min_u32_e32 v2, v5, v9
	v_max_u32_e32 v4, v8, v6
	v_max_u32_e32 v12, v5, v9
	v_min_u32_e32 v6, v8, v6
	v_max_u32_e32 v5, v10, v3
	v_min_u32_e32 v3, v10, v3
	v_max_u32_e32 v8, v4, v2
	v_min_u32_e32 v4, v4, v2
	v_min_u32_e32 v9, v7, v12
	v_min_u32_e32 v2, v5, v8
	v_max_u32_e32 v10, v3, v4
	v_max_u32_e32 v13, v11, v6
	v_min_u32_e32 v22, v10, v9
	v_max_u32_e32 v23, v13, v2
	v_min_u32_e32 v13, v13, v2
	v_max_u32_e32 v8, v5, v8
	v_min_u32_e32 v24, v3, v4
	v_max_u32_e32 v9, v10, v9
	v_max_u32_e32 v3, v8, v9
	v_max_u32_e32 v4, v13, v24
	v_max_u32_e32 v5, v7, v12
	v_min_u32_e32 v7, v8, v9
	v_min_u32_e32 v9, v13, v24
	v_ashrrev_i32_e32 v13, 31, v18
	v_bitop3_b32 v13, v13, v18, s27 bitop3:0x36
	v_ashrrev_i32_e32 v18, 31, v17
	v_bitop3_b32 v17, v18, v17, s27 bitop3:0x36
	v_ashrrev_i32_e32 v18, 31, v16
	v_bitop3_b32 v16, v18, v16, s27 bitop3:0x36
	v_ashrrev_i32_e32 v18, 31, v15
	v_min_u32_e32 v6, v11, v6
	v_ashrrev_i32_e32 v10, 31, v19
	v_ashrrev_i32_e32 v11, 31, v21
	v_ashrrev_i32_e32 v12, 31, v20
	v_bitop3_b32 v15, v18, v15, s27 bitop3:0x36
	v_ashrrev_i32_e32 v18, 31, v14
	v_bitop3_b32 v10, v10, v19, s27 bitop3:0x36
	v_bitop3_b32 v11, v11, v21, s27 bitop3:0x36
	v_bitop3_b32 v12, v12, v20, s27 bitop3:0x36
	v_bitop3_b32 v14, v18, v14, s27 bitop3:0x36
	v_and_or_b32 v10, v10, s40, v155
	v_and_or_b32 v11, v11, s40, v159
	v_and_or_b32 v12, v12, s40, v160
	v_and_or_b32 v13, v13, s40, v161
	v_and_or_b32 v17, v17, s40, v162
	v_and_or_b32 v16, v16, s40, v163
	v_and_or_b32 v15, v15, s40, v164
	v_and_or_b32 v14, v14, s40, v165
	v_max_u32_e32 v18, v10, v11
	v_min_u32_e32 v10, v10, v11
	v_max_u32_e32 v11, v12, v13
	v_min_u32_e32 v12, v12, v13
	v_max_u32_e32 v13, v17, v16
	v_min_u32_e32 v16, v17, v16
	v_max_u32_e32 v17, v15, v14
	v_min_u32_e32 v14, v15, v14
	v_max_u32_e32 v15, v18, v11
	v_min_u32_e32 v11, v18, v11
	v_max_u32_e32 v18, v10, v12
	v_min_u32_e32 v12, v10, v12
	v_max_u32_e32 v19, v13, v17
	v_min_u32_e32 v10, v13, v17
	v_max_u32_e32 v13, v16, v14
	v_min_u32_e32 v14, v16, v14
	v_max_u32_e32 v16, v18, v11
	v_min_u32_e32 v11, v18, v11
	v_max_u32_e32 v17, v13, v10
	v_min_u32_e32 v13, v13, v10
	v_max_u32_e32 v10, v15, v19
	v_min_u32_e32 v15, v15, v19
	v_max_u32_e32 v18, v16, v17
	v_min_u32_e32 v16, v16, v17
	v_max_u32_e32 v17, v11, v13
	v_min_u32_e32 v19, v11, v13
	v_max_u32_e32 v13, v12, v14
	v_min_u32_e32 v11, v12, v14
	v_max_u32_e32 v14, v17, v15
	v_min_u32_e32 v15, v17, v15
	v_max_u32_e32 v17, v13, v16
	v_min_u32_e32 v20, v13, v16
	v_max_u32_e32 v2, v23, v22
	v_min_u32_e32 v8, v23, v22
	v_max_u32_e32 v12, v18, v14
	v_min_u32_e32 v13, v18, v14
	v_max_u32_e32 v14, v17, v15
	v_min_u32_e32 v15, v17, v15
	v_max_u32_e32 v16, v20, v19
	v_min_u32_e32 v17, v20, v19
	v_mov_b32_e32 v96, 0
	s_mov_b32 s0, 0
	v_mov_b32_e32 v97, 0
